# FFN-up conv epilogue: rows unpacked once into rotating f32 window, weight loads issued before the LDS stage
# speedup vs baseline: 1.0524x; 1.0101x over previous
.LBB0_163:
	v_mov_b32_e32 v0, v191
	s_barrier
	v_and_b32_e32 v224, 15, v191
	s_lshl_b32 s9, s8, 7
	v_lshl_or_b32 v225, v224, 3, s9
	v_lshlrev_b32_e32 v226, 2, v225
	global_load_dwordx4 v[134:137], v226, s[12:13]
	global_load_dwordx4 v[138:141], v226, s[12:13] offset:16
	global_load_dwordx4 v[142:145], v226, s[16:17]
	global_load_dwordx4 v[146:149], v226, s[16:17] offset:16
	global_load_dwordx4 v[150:153], v226, s[18:19]
	global_load_dwordx4 v[154:157], v226, s[18:19] offset:16
	global_load_dwordx4 v[158:161], v226, s[20:21]
	global_load_dwordx4 v[162:165], v226, s[20:21] offset:16
	global_load_dwordx4 v[192:195], v226, s[22:23]
	global_load_dwordx4 v[196:199], v226, s[22:23] offset:16
	global_load_dwordx4 v[200:203], v226, s[24:25]
	global_load_dwordx4 v[204:207], v226, s[24:25] offset:16
	global_load_dwordx4 v[208:211], v226, s[14:15]
	global_load_dwordx4 v[212:215], v226, s[14:15] offset:16
	global_load_dwordx4 v[216:219], v226, s[26:27]
	global_load_dwordx4 v[220:223], v226, s[26:27] offset:16
	s_lshl_b32 s6, s67, 6
	v_and_b32_e32 v130, 15, v0
	v_or_b32_e32 v132, s70, v130
	s_movk_i32 s7, 0x220
	v_and_b32_e32 v131, 48, v0
	s_add_i32 s6, s6, 0
	v_mul_lo_u32 v132, v132, s7
	v_add3_u32 v131, s6, v131, v132
	v_cvt_pk_bf16_f32 v62, v62, v63
	v_cvt_pk_bf16_f32 v63, v64, v65
	v_cvt_pk_bf16_f32 v64, v58, v59
	v_add_u32_e32 v58, 0x11100, v131
	v_cvt_pk_bf16_f32 v46, v46, v47
	v_cvt_pk_bf16_f32 v47, v48, v49
	v_cvt_pk_bf16_f32 v48, v42, v43
	v_cvt_pk_bf16_f32 v49, v44, v45
	ds_write_b128 v58, v[46:49]
	v_add_u32_e32 v46, 0x13200, v131
	v_cvt_pk_bf16_f32 v42, v54, v55
	v_cvt_pk_bf16_f32 v43, v56, v57
	v_cvt_pk_bf16_f32 v44, v50, v51
	v_cvt_pk_bf16_f32 v45, v52, v53
	ds_write_b128 v46, v[42:45]
	v_add_u32_e32 v42, 0x13300, v131
	v_cvt_pk_bf16_f32 v30, v30, v31
	v_cvt_pk_bf16_f32 v31, v32, v33
	v_cvt_pk_bf16_f32 v32, v26, v27
	v_cvt_pk_bf16_f32 v33, v28, v29
	v_cvt_pk_bf16_f32 v94, v94, v95
	v_cvt_pk_bf16_f32 v95, v96, v97
	v_cvt_pk_bf16_f32 v96, v90, v91
	v_cvt_pk_bf16_f32 v97, v92, v93
	ds_write_b128 v42, v[30:33]
	v_add_u32_e32 v30, 0x15400, v131
	v_cvt_pk_bf16_f32 v26, v38, v39
	v_cvt_pk_bf16_f32 v27, v40, v41
	v_cvt_pk_bf16_f32 v28, v34, v35
	v_cvt_pk_bf16_f32 v29, v36, v37
	s_lshl_b32 s6, s8, 7
	ds_write_b128 v131, v[94:97] offset:8960
	ds_write_b128 v30, v[26:29]
	v_add_u32_e32 v26, 0x15500, v131
	v_cvt_pk_bf16_f32 v14, v14, v15
	v_cvt_pk_bf16_f32 v15, v16, v17
	v_cvt_pk_bf16_f32 v16, v10, v11
	v_cvt_pk_bf16_f32 v17, v12, v13
	v_lshl_or_b32 v94, v130, 3, s6
	ds_write_b128 v26, v[14:17]
	v_add_u32_e32 v14, 0x17600, v131
	v_cvt_pk_bf16_f32 v10, v22, v23
	v_cvt_pk_bf16_f32 v11, v24, v25
	v_cvt_pk_bf16_f32 v12, v18, v19
	v_cvt_pk_bf16_f32 v13, v20, v21
	v_ashrrev_i32_e32 v95, 31, v94
	v_cvt_pk_bf16_f32 v126, v126, v127
	v_cvt_pk_bf16_f32 v127, v128, v129
	v_cvt_pk_bf16_f32 v128, v122, v123
	v_cvt_pk_bf16_f32 v129, v124, v125
	v_cvt_pk_bf16_f32 v110, v110, v111
	v_cvt_pk_bf16_f32 v111, v112, v113
	v_cvt_pk_bf16_f32 v112, v106, v107
	v_cvt_pk_bf16_f32 v113, v108, v109
	v_cvt_pk_bf16_f32 v106, v118, v119
	v_cvt_pk_bf16_f32 v107, v120, v121
	v_cvt_pk_bf16_f32 v108, v114, v115
	v_cvt_pk_bf16_f32 v109, v116, v117
	v_cvt_pk_bf16_f32 v90, v102, v103
	v_cvt_pk_bf16_f32 v91, v104, v105
	v_cvt_pk_bf16_f32 v92, v98, v99
	v_cvt_pk_bf16_f32 v93, v100, v101
	v_cvt_pk_bf16_f32 v78, v78, v79
	v_cvt_pk_bf16_f32 v79, v80, v81
	v_cvt_pk_bf16_f32 v80, v74, v75
	v_cvt_pk_bf16_f32 v81, v76, v77
	v_cvt_pk_bf16_f32 v74, v86, v87
	v_cvt_pk_bf16_f32 v75, v88, v89
	v_cvt_pk_bf16_f32 v76, v82, v83
	v_cvt_pk_bf16_f32 v77, v84, v85
	v_cvt_pk_bf16_f32 v70, v70, v71
	v_cvt_pk_bf16_f32 v71, v72, v73
	v_cvt_pk_bf16_f32 v72, v66, v67
	v_cvt_pk_bf16_f32 v73, v68, v69
	v_add_u32_e32 v66, 0x11000, v131
	v_cvt_pk_bf16_f32 v65, v60, v61
	ds_write_b128 v14, v[10:13]
	v_add_u32_e32 v10, 0x17700, v131
	v_cvt_pk_bf16_f32 v6, v6, v7
	v_cvt_pk_bf16_f32 v7, v8, v9
	v_cvt_pk_bf16_f32 v8, v2, v3
	v_cvt_pk_bf16_f32 v9, v4, v5
	v_lshlrev_b64 v[22:23], 2, v[94:95]
	ds_write_b128 v131, v[126:129]
	ds_write_b128 v131, v[110:113] offset:256
	ds_write_b128 v131, v[106:109] offset:8704
	ds_write_b128 v131, v[90:93] offset:17408
	ds_write_b128 v131, v[78:81] offset:17664
	ds_write_b128 v131, v[74:77] offset:26112
	ds_write_b128 v131, v[70:73] offset:26368
	ds_write_b128 v66, v[62:65]
	ds_write_b128 v10, v[6:9]
	v_lshl_add_u64 v[2:3], s[12:13], 0, v[22:23]
	v_lshl_add_u64 v[6:7], s[16:17], 0, v[22:23]
	s_waitcnt lgkmcnt(0)
	s_waitcnt vmcnt(0) lgkmcnt(0)
	s_barrier
	v_and_b32_e32 v47, 15, v191
	v_lshrrev_b32_e32 v48, 4, v191
	s_lshl_b32 s6, s8, 7
	v_lshl_or_b32 v44, v47, 3, s6
	v_lshlrev_b32_e32 v49, 3, v48
	s_movk_i32 s44, 0x220
	s_movk_i32 s49, 0x4000
	v_mul_lo_u32 v54, v49, s44
	v_lshl_add_u32 v54, v47, 4, v54
	v_add_u32_e32 v49, 1, v49
	s_mul_i32 s9, s30, 0xfe
	s_add_i32 s9, s9, -1
	v_add_u32_e32 v45, s9, v49
	v_readlane_b32 s28, v255, 19
	s_movk_i32 s38, 0x1600
	v_mov_b64_e32 v[50:51], s[10:11]
	v_mad_i64_i32 v[50:51], s[6:7], v45, s38, v[50:51]
	v_lshlrev_b32_e32 v52, 1, v44
	v_mov_b32_e32 v53, 0
	v_lshl_add_u64 v[50:51], v[50:51], 0, v[52:53]
	s_mov_b32 s39, 0
	v_mov_b32_e32 v42, 0xbfb8aa3b
	ds_read_b128 v[114:117], v54 offset:0
	ds_read_b128 v[118:121], v54 offset:256
	ds_read_b128 v[122:125], v54 offset:544
	ds_read_b128 v[126:129], v54 offset:800
	s_waitcnt lgkmcnt(2)
	v_lshlrev_b32_e32 v66, 16, v114
	v_and_b32_e32 v67, 0xffff0000, v114
	v_lshlrev_b32_e32 v68, 16, v115
	v_and_b32_e32 v69, 0xffff0000, v115
	v_lshlrev_b32_e32 v70, 16, v116
	v_and_b32_e32 v71, 0xffff0000, v116
	v_lshlrev_b32_e32 v72, 16, v117
	v_and_b32_e32 v73, 0xffff0000, v117
	v_lshlrev_b32_e32 v74, 16, v118
	v_and_b32_e32 v75, 0xffff0000, v118
	v_lshlrev_b32_e32 v76, 16, v119
	v_and_b32_e32 v77, 0xffff0000, v119
	v_lshlrev_b32_e32 v78, 16, v120
	v_and_b32_e32 v79, 0xffff0000, v120
	v_lshlrev_b32_e32 v80, 16, v121
	v_and_b32_e32 v81, 0xffff0000, v121
	ds_read_b128 v[114:117], v54 offset:1088
	ds_read_b128 v[118:121], v54 offset:1344
	s_waitcnt lgkmcnt(2)
	v_lshlrev_b32_e32 v82, 16, v122
	v_and_b32_e32 v83, 0xffff0000, v122
	v_lshlrev_b32_e32 v84, 16, v123
	v_and_b32_e32 v85, 0xffff0000, v123
	v_lshlrev_b32_e32 v86, 16, v124
	v_and_b32_e32 v87, 0xffff0000, v124
	v_lshlrev_b32_e32 v88, 16, v125
	v_and_b32_e32 v89, 0xffff0000, v125
	v_lshlrev_b32_e32 v90, 16, v126
	v_and_b32_e32 v91, 0xffff0000, v126
	v_lshlrev_b32_e32 v92, 16, v127
	v_and_b32_e32 v93, 0xffff0000, v127
	v_lshlrev_b32_e32 v94, 16, v128
	v_and_b32_e32 v95, 0xffff0000, v128
	v_lshlrev_b32_e32 v96, 16, v129
	v_and_b32_e32 v97, 0xffff0000, v129
	s_waitcnt vmcnt(0)
	s_waitcnt lgkmcnt(0)
	v_lshlrev_b32_e32 v98, 16, v114
	v_and_b32_e32 v99, 0xffff0000, v114
	v_lshlrev_b32_e32 v100, 16, v115
	v_and_b32_e32 v101, 0xffff0000, v115
	v_lshlrev_b32_e32 v102, 16, v116
	v_and_b32_e32 v103, 0xffff0000, v116
	v_lshlrev_b32_e32 v104, 16, v117
	v_and_b32_e32 v105, 0xffff0000, v117
	v_lshlrev_b32_e32 v106, 16, v118
	v_and_b32_e32 v107, 0xffff0000, v118
	v_lshlrev_b32_e32 v108, 16, v119
	v_and_b32_e32 v109, 0xffff0000, v119
	v_lshlrev_b32_e32 v110, 16, v120
	v_and_b32_e32 v111, 0xffff0000, v120
	v_lshlrev_b32_e32 v112, 16, v121
	v_and_b32_e32 v113, 0xffff0000, v121
	ds_read_b128 v[122:125], v54 offset:1632
	ds_read_b128 v[126:129], v54 offset:1888
	s_movk_i32 s6, 255
	v_cmp_gt_i32_e32 vcc, s6, v49
	s_mov_b32 s6, s28
	v_cmp_gt_i32_e64 s[6:7], s6, v45
	s_and_b64 s[6:7], vcc, s[6:7]
	s_and_saveexec_b64 s[28:29], s[6:7]
	s_cbranch_execz .Luc_skip0
	v_add_u32_e32 v52, 0, v45
	v_mov_b32_e32 v53, 0xff
	v_cmp_gt_i32_e32 vcc, s49, v52
	v_mov_b32_e32 v46, 0xfff
	s_nop 0
	v_cndmask_b32_e32 v53, v53, v46, vcc
	v_and_b32_e32 v52, v52, v53
	v_cmp_ne_u32_e32 vcc, 0, v52
	v_cmp_ne_u32_e64 s[6:7], v52, v53
	s_mov_b64 s[78:79], 0
	s_and_b64 s[76:77], vcc, s[6:7]
	s_xor_b64 s[76:77], s[76:77], exec
	s_cbranch_scc0 .Luc_fast0
	v_cndmask_b32_e32 v66, 0, v66, vcc
	v_cndmask_b32_e32 v67, 0, v67, vcc
	v_cndmask_b32_e32 v68, 0, v68, vcc
	v_cndmask_b32_e32 v69, 0, v69, vcc
	v_cndmask_b32_e32 v70, 0, v70, vcc
	v_cndmask_b32_e32 v71, 0, v71, vcc
	v_cndmask_b32_e32 v72, 0, v72, vcc
	v_cndmask_b32_e32 v73, 0, v73, vcc
	v_cndmask_b32_e32 v74, 0, v74, vcc
	v_cndmask_b32_e32 v75, 0, v75, vcc
	v_cndmask_b32_e32 v76, 0, v76, vcc
	v_cndmask_b32_e32 v77, 0, v77, vcc
	v_cndmask_b32_e32 v78, 0, v78, vcc
	v_cndmask_b32_e32 v79, 0, v79, vcc
	v_cndmask_b32_e32 v80, 0, v80, vcc
	v_cndmask_b32_e32 v81, 0, v81, vcc
	v_mov_b64_e32 v[2:3], v[98:99]
	v_mov_b64_e32 v[4:5], v[100:101]
	v_mov_b64_e32 v[6:7], v[102:103]
	v_mov_b64_e32 v[8:9], v[104:105]
	v_mov_b64_e32 v[10:11], v[106:107]
	v_mov_b64_e32 v[12:13], v[108:109]
	v_mov_b64_e32 v[14:15], v[110:111]
	v_mov_b64_e32 v[16:17], v[112:113]
	v_cndmask_b32_e64 v98, 0, v98, s[6:7]
	v_cndmask_b32_e64 v99, 0, v99, s[6:7]
	v_cndmask_b32_e64 v100, 0, v100, s[6:7]
	v_cndmask_b32_e64 v101, 0, v101, s[6:7]
	v_cndmask_b32_e64 v102, 0, v102, s[6:7]
	v_cndmask_b32_e64 v103, 0, v103, s[6:7]
	v_cndmask_b32_e64 v104, 0, v104, s[6:7]
	v_cndmask_b32_e64 v105, 0, v105, s[6:7]
	v_cndmask_b32_e64 v106, 0, v106, s[6:7]
	v_cndmask_b32_e64 v107, 0, v107, s[6:7]
	v_cndmask_b32_e64 v108, 0, v108, s[6:7]
	v_cndmask_b32_e64 v109, 0, v109, s[6:7]
	v_cndmask_b32_e64 v110, 0, v110, s[6:7]
	v_cndmask_b32_e64 v111, 0, v111, s[6:7]
	v_cndmask_b32_e64 v112, 0, v112, s[6:7]
	v_cndmask_b32_e64 v113, 0, v113, s[6:7]
	s_mov_b64 s[78:79], -1
.Luc_fast0:
	v_pk_fma_f32 v[18:19], v[150:151], v[82:83], v[208:209]
	v_pk_fma_f32 v[26:27], v[158:159], v[90:91], v[216:217]
	v_pk_fma_f32 v[20:21], v[152:153], v[84:85], v[210:211]
	v_pk_fma_f32 v[28:29], v[160:161], v[92:93], v[218:219]
	v_pk_fma_f32 v[22:23], v[154:155], v[86:87], v[212:213]
	v_pk_fma_f32 v[30:31], v[162:163], v[94:95], v[220:221]
	v_pk_fma_f32 v[24:25], v[156:157], v[88:89], v[214:215]
	v_pk_fma_f32 v[32:33], v[164:165], v[96:97], v[222:223]
	v_pk_fma_f32 v[18:19], v[134:135], v[66:67], v[18:19]
	v_pk_fma_f32 v[26:27], v[142:143], v[74:75], v[26:27]
	v_pk_fma_f32 v[20:21], v[136:137], v[68:69], v[20:21]
	v_pk_fma_f32 v[28:29], v[144:145], v[76:77], v[28:29]
	v_pk_fma_f32 v[22:23], v[138:139], v[70:71], v[22:23]
	v_pk_fma_f32 v[30:31], v[146:147], v[78:79], v[30:31]
	v_pk_fma_f32 v[24:25], v[140:141], v[72:73], v[24:25]
	v_pk_fma_f32 v[32:33], v[148:149], v[80:81], v[32:33]
	v_pk_fma_f32 v[18:19], v[192:193], v[98:99], v[18:19]
	v_pk_fma_f32 v[26:27], v[200:201], v[106:107], v[26:27]
	v_pk_fma_f32 v[20:21], v[194:195], v[100:101], v[20:21]
	v_pk_fma_f32 v[28:29], v[202:203], v[108:109], v[28:29]
	v_pk_fma_f32 v[22:23], v[196:197], v[102:103], v[22:23]
	v_pk_fma_f32 v[30:31], v[204:205], v[110:111], v[30:31]
	v_pk_fma_f32 v[24:25], v[198:199], v[104:105], v[24:25]
	v_pk_fma_f32 v[32:33], v[206:207], v[112:113], v[32:33]
	v_pk_mul_f32 v[34:35], v[18:19], v[42:43] op_sel_hi:[1,0]
	v_pk_mul_f32 v[36:37], v[20:21], v[42:43] op_sel_hi:[1,0]
	v_pk_mul_f32 v[38:39], v[22:23], v[42:43] op_sel_hi:[1,0]
	v_pk_mul_f32 v[40:41], v[24:25], v[42:43] op_sel_hi:[1,0]
	v_exp_f32_e32 v34, v34
	v_exp_f32_e32 v35, v35
	v_exp_f32_e32 v36, v36
	v_exp_f32_e32 v37, v37
	v_exp_f32_e32 v38, v38
	v_exp_f32_e32 v39, v39
	v_exp_f32_e32 v40, v40
	v_exp_f32_e32 v41, v41
	v_pk_add_f32 v[34:35], v[34:35], 1.0 op_sel_hi:[1,0]
	v_pk_add_f32 v[36:37], v[36:37], 1.0 op_sel_hi:[1,0]
	v_pk_add_f32 v[38:39], v[38:39], 1.0 op_sel_hi:[1,0]
	v_pk_add_f32 v[40:41], v[40:41], 1.0 op_sel_hi:[1,0]
	v_rcp_f32_e32 v34, v34
	v_rcp_f32_e32 v35, v35
	v_rcp_f32_e32 v36, v36
	v_rcp_f32_e32 v37, v37
	v_rcp_f32_e32 v38, v38
	v_rcp_f32_e32 v39, v39
	v_rcp_f32_e32 v40, v40
	v_rcp_f32_e32 v41, v41
	v_pk_mul_f32 v[18:19], v[18:19], v[34:35]
	v_pk_mul_f32 v[20:21], v[20:21], v[36:37]
	v_pk_mul_f32 v[22:23], v[22:23], v[38:39]
	v_pk_mul_f32 v[24:25], v[24:25], v[40:41]
	v_pk_mul_f32 v[18:19], v[26:27], v[18:19]
	v_pk_mul_f32 v[20:21], v[28:29], v[20:21]
	v_pk_mul_f32 v[22:23], v[30:31], v[22:23]
	v_pk_mul_f32 v[24:25], v[32:33], v[24:25]
	v_cvt_pk_bf16_f32 v34, v18, v19
	v_cvt_pk_bf16_f32 v35, v20, v21
	v_cvt_pk_bf16_f32 v36, v22, v23
	v_cvt_pk_bf16_f32 v37, v24, v25
	global_store_dwordx4 v[50:51], v[34:37], off nt
	s_and_b64 vcc, exec, s[78:79]
	s_cbranch_vccz .Luc_skip0
	v_mov_b64_e32 v[98:99], v[2:3]
	v_mov_b64_e32 v[100:101], v[4:5]
	v_mov_b64_e32 v[102:103], v[6:7]
	v_mov_b64_e32 v[104:105], v[8:9]
	v_mov_b64_e32 v[106:107], v[10:11]
	v_mov_b64_e32 v[108:109], v[12:13]
	v_mov_b64_e32 v[110:111], v[14:15]
	v_mov_b64_e32 v[112:113], v[16:17]
.Luc_skip0:
	s_or_b64 exec, exec, s[28:29]
	v_readlane_b32 s28, v255, 19
	v_lshl_add_u64 v[50:51], v[50:51], 0, s[38:39]
	s_waitcnt lgkmcnt(0)
	v_lshlrev_b32_e32 v66, 16, v122
	v_and_b32_e32 v67, 0xffff0000, v122
	v_lshlrev_b32_e32 v68, 16, v123
	v_and_b32_e32 v69, 0xffff0000, v123
	v_lshlrev_b32_e32 v70, 16, v124
	v_and_b32_e32 v71, 0xffff0000, v124
	v_lshlrev_b32_e32 v72, 16, v125
	v_and_b32_e32 v73, 0xffff0000, v125
	v_lshlrev_b32_e32 v74, 16, v126
	v_and_b32_e32 v75, 0xffff0000, v126
	v_lshlrev_b32_e32 v76, 16, v127
	v_and_b32_e32 v77, 0xffff0000, v127
	v_lshlrev_b32_e32 v78, 16, v128
	v_and_b32_e32 v79, 0xffff0000, v128
	v_lshlrev_b32_e32 v80, 16, v129
	v_and_b32_e32 v81, 0xffff0000, v129
	ds_read_b128 v[114:117], v54 offset:2176
	ds_read_b128 v[118:121], v54 offset:2432
	s_movk_i32 s6, 254
	v_cmp_gt_i32_e32 vcc, s6, v49
	s_sub_i32 s6, s28, 1
	v_cmp_gt_i32_e64 s[6:7], s6, v45
	s_and_b64 s[6:7], vcc, s[6:7]
	s_and_saveexec_b64 s[28:29], s[6:7]
	s_cbranch_execz .Luc_skip1
	v_add_u32_e32 v52, 1, v45
	v_mov_b32_e32 v53, 0xff
	v_cmp_gt_i32_e32 vcc, s49, v52
	v_mov_b32_e32 v46, 0xfff
	s_nop 0
	v_cndmask_b32_e32 v53, v53, v46, vcc
	v_and_b32_e32 v52, v52, v53
	v_cmp_ne_u32_e32 vcc, 0, v52
	v_cmp_ne_u32_e64 s[6:7], v52, v53
	s_mov_b64 s[78:79], 0
	s_and_b64 s[76:77], vcc, s[6:7]
	s_xor_b64 s[76:77], s[76:77], exec
	s_cbranch_scc0 .Luc_fast1
	v_cndmask_b32_e32 v82, 0, v82, vcc
	v_cndmask_b32_e32 v83, 0, v83, vcc
	v_cndmask_b32_e32 v84, 0, v84, vcc
	v_cndmask_b32_e32 v85, 0, v85, vcc
	v_cndmask_b32_e32 v86, 0, v86, vcc
	v_cndmask_b32_e32 v87, 0, v87, vcc
	v_cndmask_b32_e32 v88, 0, v88, vcc
	v_cndmask_b32_e32 v89, 0, v89, vcc
	v_cndmask_b32_e32 v90, 0, v90, vcc
	v_cndmask_b32_e32 v91, 0, v91, vcc
	v_cndmask_b32_e32 v92, 0, v92, vcc
	v_cndmask_b32_e32 v93, 0, v93, vcc
	v_cndmask_b32_e32 v94, 0, v94, vcc
	v_cndmask_b32_e32 v95, 0, v95, vcc
	v_cndmask_b32_e32 v96, 0, v96, vcc
	v_cndmask_b32_e32 v97, 0, v97, vcc
	v_mov_b64_e32 v[2:3], v[66:67]
	v_mov_b64_e32 v[4:5], v[68:69]
	v_mov_b64_e32 v[6:7], v[70:71]
	v_mov_b64_e32 v[8:9], v[72:73]
	v_mov_b64_e32 v[10:11], v[74:75]
	v_mov_b64_e32 v[12:13], v[76:77]
	v_mov_b64_e32 v[14:15], v[78:79]
	v_mov_b64_e32 v[16:17], v[80:81]
	v_cndmask_b32_e64 v66, 0, v66, s[6:7]
	v_cndmask_b32_e64 v67, 0, v67, s[6:7]
	v_cndmask_b32_e64 v68, 0, v68, s[6:7]
	v_cndmask_b32_e64 v69, 0, v69, s[6:7]
	v_cndmask_b32_e64 v70, 0, v70, s[6:7]
	v_cndmask_b32_e64 v71, 0, v71, s[6:7]
	v_cndmask_b32_e64 v72, 0, v72, s[6:7]
	v_cndmask_b32_e64 v73, 0, v73, s[6:7]
	v_cndmask_b32_e64 v74, 0, v74, s[6:7]
	v_cndmask_b32_e64 v75, 0, v75, s[6:7]
	v_cndmask_b32_e64 v76, 0, v76, s[6:7]
	v_cndmask_b32_e64 v77, 0, v77, s[6:7]
	v_cndmask_b32_e64 v78, 0, v78, s[6:7]
	v_cndmask_b32_e64 v79, 0, v79, s[6:7]
	v_cndmask_b32_e64 v80, 0, v80, s[6:7]
	v_cndmask_b32_e64 v81, 0, v81, s[6:7]
	s_mov_b64 s[78:79], -1
.Luc_fast1:
	v_pk_fma_f32 v[18:19], v[150:151], v[98:99], v[208:209]
	v_pk_fma_f32 v[26:27], v[158:159], v[106:107], v[216:217]
	v_pk_fma_f32 v[20:21], v[152:153], v[100:101], v[210:211]
	v_pk_fma_f32 v[28:29], v[160:161], v[108:109], v[218:219]
	v_pk_fma_f32 v[22:23], v[154:155], v[102:103], v[212:213]
	v_pk_fma_f32 v[30:31], v[162:163], v[110:111], v[220:221]
	v_pk_fma_f32 v[24:25], v[156:157], v[104:105], v[214:215]
	v_pk_fma_f32 v[32:33], v[164:165], v[112:113], v[222:223]
	v_pk_fma_f32 v[18:19], v[134:135], v[82:83], v[18:19]
	v_pk_fma_f32 v[26:27], v[142:143], v[90:91], v[26:27]
	v_pk_fma_f32 v[20:21], v[136:137], v[84:85], v[20:21]
	v_pk_fma_f32 v[28:29], v[144:145], v[92:93], v[28:29]
	v_pk_fma_f32 v[22:23], v[138:139], v[86:87], v[22:23]
	v_pk_fma_f32 v[30:31], v[146:147], v[94:95], v[30:31]
	v_pk_fma_f32 v[24:25], v[140:141], v[88:89], v[24:25]
	v_pk_fma_f32 v[32:33], v[148:149], v[96:97], v[32:33]
	v_pk_fma_f32 v[18:19], v[192:193], v[66:67], v[18:19]
	v_pk_fma_f32 v[26:27], v[200:201], v[74:75], v[26:27]
	v_pk_fma_f32 v[20:21], v[194:195], v[68:69], v[20:21]
	v_pk_fma_f32 v[28:29], v[202:203], v[76:77], v[28:29]
	v_pk_fma_f32 v[22:23], v[196:197], v[70:71], v[22:23]
	v_pk_fma_f32 v[30:31], v[204:205], v[78:79], v[30:31]
	v_pk_fma_f32 v[24:25], v[198:199], v[72:73], v[24:25]
	v_pk_fma_f32 v[32:33], v[206:207], v[80:81], v[32:33]
	v_pk_mul_f32 v[34:35], v[18:19], v[42:43] op_sel_hi:[1,0]
	v_pk_mul_f32 v[36:37], v[20:21], v[42:43] op_sel_hi:[1,0]
	v_pk_mul_f32 v[38:39], v[22:23], v[42:43] op_sel_hi:[1,0]
	v_pk_mul_f32 v[40:41], v[24:25], v[42:43] op_sel_hi:[1,0]
	v_exp_f32_e32 v34, v34
	v_exp_f32_e32 v35, v35
	v_exp_f32_e32 v36, v36
	v_exp_f32_e32 v37, v37
	v_exp_f32_e32 v38, v38
	v_exp_f32_e32 v39, v39
	v_exp_f32_e32 v40, v40
	v_exp_f32_e32 v41, v41
	v_pk_add_f32 v[34:35], v[34:35], 1.0 op_sel_hi:[1,0]
	v_pk_add_f32 v[36:37], v[36:37], 1.0 op_sel_hi:[1,0]
	v_pk_add_f32 v[38:39], v[38:39], 1.0 op_sel_hi:[1,0]
	v_pk_add_f32 v[40:41], v[40:41], 1.0 op_sel_hi:[1,0]
	v_rcp_f32_e32 v34, v34
	v_rcp_f32_e32 v35, v35
	v_rcp_f32_e32 v36, v36
	v_rcp_f32_e32 v37, v37
	v_rcp_f32_e32 v38, v38
	v_rcp_f32_e32 v39, v39
	v_rcp_f32_e32 v40, v40
	v_rcp_f32_e32 v41, v41
	v_pk_mul_f32 v[18:19], v[18:19], v[34:35]
	v_pk_mul_f32 v[20:21], v[20:21], v[36:37]
	v_pk_mul_f32 v[22:23], v[22:23], v[38:39]
	v_pk_mul_f32 v[24:25], v[24:25], v[40:41]
	v_pk_mul_f32 v[18:19], v[26:27], v[18:19]
	v_pk_mul_f32 v[20:21], v[28:29], v[20:21]
	v_pk_mul_f32 v[22:23], v[30:31], v[22:23]
	v_pk_mul_f32 v[24:25], v[32:33], v[24:25]
	v_cvt_pk_bf16_f32 v34, v18, v19
	v_cvt_pk_bf16_f32 v35, v20, v21
	v_cvt_pk_bf16_f32 v36, v22, v23
	v_cvt_pk_bf16_f32 v37, v24, v25
	global_store_dwordx4 v[50:51], v[34:37], off nt
	s_and_b64 vcc, exec, s[78:79]
	s_cbranch_vccz .Luc_skip1
	v_mov_b64_e32 v[66:67], v[2:3]
	v_mov_b64_e32 v[68:69], v[4:5]
	v_mov_b64_e32 v[70:71], v[6:7]
	v_mov_b64_e32 v[72:73], v[8:9]
	v_mov_b64_e32 v[74:75], v[10:11]
	v_mov_b64_e32 v[76:77], v[12:13]
	v_mov_b64_e32 v[78:79], v[14:15]
	v_mov_b64_e32 v[80:81], v[16:17]
.Luc_skip1:
	s_or_b64 exec, exec, s[28:29]
	v_readlane_b32 s28, v255, 19
	v_lshl_add_u64 v[50:51], v[50:51], 0, s[38:39]
	s_waitcnt lgkmcnt(0)
	v_lshlrev_b32_e32 v82, 16, v114
	v_and_b32_e32 v83, 0xffff0000, v114
	v_lshlrev_b32_e32 v84, 16, v115
	v_and_b32_e32 v85, 0xffff0000, v115
	v_lshlrev_b32_e32 v86, 16, v116
	v_and_b32_e32 v87, 0xffff0000, v116
	v_lshlrev_b32_e32 v88, 16, v117
	v_and_b32_e32 v89, 0xffff0000, v117
	v_lshlrev_b32_e32 v90, 16, v118
	v_and_b32_e32 v91, 0xffff0000, v118
	v_lshlrev_b32_e32 v92, 16, v119
	v_and_b32_e32 v93, 0xffff0000, v119
	v_lshlrev_b32_e32 v94, 16, v120
	v_and_b32_e32 v95, 0xffff0000, v120
	v_lshlrev_b32_e32 v96, 16, v121
	v_and_b32_e32 v97, 0xffff0000, v121
	ds_read_b128 v[122:125], v54 offset:2720
	ds_read_b128 v[126:129], v54 offset:2976
	s_movk_i32 s6, 253
	v_cmp_gt_i32_e32 vcc, s6, v49
	s_sub_i32 s6, s28, 2
	v_cmp_gt_i32_e64 s[6:7], s6, v45
	s_and_b64 s[6:7], vcc, s[6:7]
	s_and_saveexec_b64 s[28:29], s[6:7]
	s_cbranch_execz .Luc_skip2
	v_add_u32_e32 v52, 2, v45
	v_mov_b32_e32 v53, 0xff
	v_cmp_gt_i32_e32 vcc, s49, v52
	v_mov_b32_e32 v46, 0xfff
	s_nop 0
	v_cndmask_b32_e32 v53, v53, v46, vcc
	v_and_b32_e32 v52, v52, v53
	v_cmp_ne_u32_e32 vcc, 0, v52
	v_cmp_ne_u32_e64 s[6:7], v52, v53
	s_mov_b64 s[78:79], 0
	s_and_b64 s[76:77], vcc, s[6:7]
	s_xor_b64 s[76:77], s[76:77], exec
	s_cbranch_scc0 .Luc_fast2
	v_cndmask_b32_e32 v98, 0, v98, vcc
	v_cndmask_b32_e32 v99, 0, v99, vcc
	v_cndmask_b32_e32 v100, 0, v100, vcc
	v_cndmask_b32_e32 v101, 0, v101, vcc
	v_cndmask_b32_e32 v102, 0, v102, vcc
	v_cndmask_b32_e32 v103, 0, v103, vcc
	v_cndmask_b32_e32 v104, 0, v104, vcc
	v_cndmask_b32_e32 v105, 0, v105, vcc
	v_cndmask_b32_e32 v106, 0, v106, vcc
	v_cndmask_b32_e32 v107, 0, v107, vcc
	v_cndmask_b32_e32 v108, 0, v108, vcc
	v_cndmask_b32_e32 v109, 0, v109, vcc
	v_cndmask_b32_e32 v110, 0, v110, vcc
	v_cndmask_b32_e32 v111, 0, v111, vcc
	v_cndmask_b32_e32 v112, 0, v112, vcc
	v_cndmask_b32_e32 v113, 0, v113, vcc
	v_mov_b64_e32 v[2:3], v[82:83]
	v_mov_b64_e32 v[4:5], v[84:85]
	v_mov_b64_e32 v[6:7], v[86:87]
	v_mov_b64_e32 v[8:9], v[88:89]
	v_mov_b64_e32 v[10:11], v[90:91]
	v_mov_b64_e32 v[12:13], v[92:93]
	v_mov_b64_e32 v[14:15], v[94:95]
	v_mov_b64_e32 v[16:17], v[96:97]
	v_cndmask_b32_e64 v82, 0, v82, s[6:7]
	v_cndmask_b32_e64 v83, 0, v83, s[6:7]
	v_cndmask_b32_e64 v84, 0, v84, s[6:7]
	v_cndmask_b32_e64 v85, 0, v85, s[6:7]
	v_cndmask_b32_e64 v86, 0, v86, s[6:7]
	v_cndmask_b32_e64 v87, 0, v87, s[6:7]
	v_cndmask_b32_e64 v88, 0, v88, s[6:7]
	v_cndmask_b32_e64 v89, 0, v89, s[6:7]
	v_cndmask_b32_e64 v90, 0, v90, s[6:7]
	v_cndmask_b32_e64 v91, 0, v91, s[6:7]
	v_cndmask_b32_e64 v92, 0, v92, s[6:7]
	v_cndmask_b32_e64 v93, 0, v93, s[6:7]
	v_cndmask_b32_e64 v94, 0, v94, s[6:7]
	v_cndmask_b32_e64 v95, 0, v95, s[6:7]
	v_cndmask_b32_e64 v96, 0, v96, s[6:7]
	v_cndmask_b32_e64 v97, 0, v97, s[6:7]
	s_mov_b64 s[78:79], -1
.Luc_fast2:
	v_pk_fma_f32 v[18:19], v[150:151], v[66:67], v[208:209]
	v_pk_fma_f32 v[26:27], v[158:159], v[74:75], v[216:217]
	v_pk_fma_f32 v[20:21], v[152:153], v[68:69], v[210:211]
	v_pk_fma_f32 v[28:29], v[160:161], v[76:77], v[218:219]
	v_pk_fma_f32 v[22:23], v[154:155], v[70:71], v[212:213]
	v_pk_fma_f32 v[30:31], v[162:163], v[78:79], v[220:221]
	v_pk_fma_f32 v[24:25], v[156:157], v[72:73], v[214:215]
	v_pk_fma_f32 v[32:33], v[164:165], v[80:81], v[222:223]
	v_pk_fma_f32 v[18:19], v[134:135], v[98:99], v[18:19]
	v_pk_fma_f32 v[26:27], v[142:143], v[106:107], v[26:27]
	v_pk_fma_f32 v[20:21], v[136:137], v[100:101], v[20:21]
	v_pk_fma_f32 v[28:29], v[144:145], v[108:109], v[28:29]
	v_pk_fma_f32 v[22:23], v[138:139], v[102:103], v[22:23]
	v_pk_fma_f32 v[30:31], v[146:147], v[110:111], v[30:31]
	v_pk_fma_f32 v[24:25], v[140:141], v[104:105], v[24:25]
	v_pk_fma_f32 v[32:33], v[148:149], v[112:113], v[32:33]
	v_pk_fma_f32 v[18:19], v[192:193], v[82:83], v[18:19]
	v_pk_fma_f32 v[26:27], v[200:201], v[90:91], v[26:27]
	v_pk_fma_f32 v[20:21], v[194:195], v[84:85], v[20:21]
	v_pk_fma_f32 v[28:29], v[202:203], v[92:93], v[28:29]
	v_pk_fma_f32 v[22:23], v[196:197], v[86:87], v[22:23]
	v_pk_fma_f32 v[30:31], v[204:205], v[94:95], v[30:31]
	v_pk_fma_f32 v[24:25], v[198:199], v[88:89], v[24:25]
	v_pk_fma_f32 v[32:33], v[206:207], v[96:97], v[32:33]
	v_pk_mul_f32 v[34:35], v[18:19], v[42:43] op_sel_hi:[1,0]
	v_pk_mul_f32 v[36:37], v[20:21], v[42:43] op_sel_hi:[1,0]
	v_pk_mul_f32 v[38:39], v[22:23], v[42:43] op_sel_hi:[1,0]
	v_pk_mul_f32 v[40:41], v[24:25], v[42:43] op_sel_hi:[1,0]
	v_exp_f32_e32 v34, v34
	v_exp_f32_e32 v35, v35
	v_exp_f32_e32 v36, v36
	v_exp_f32_e32 v37, v37
	v_exp_f32_e32 v38, v38
	v_exp_f32_e32 v39, v39
	v_exp_f32_e32 v40, v40
	v_exp_f32_e32 v41, v41
	v_pk_add_f32 v[34:35], v[34:35], 1.0 op_sel_hi:[1,0]
	v_pk_add_f32 v[36:37], v[36:37], 1.0 op_sel_hi:[1,0]
	v_pk_add_f32 v[38:39], v[38:39], 1.0 op_sel_hi:[1,0]
	v_pk_add_f32 v[40:41], v[40:41], 1.0 op_sel_hi:[1,0]
	v_rcp_f32_e32 v34, v34
	v_rcp_f32_e32 v35, v35
	v_rcp_f32_e32 v36, v36
	v_rcp_f32_e32 v37, v37
	v_rcp_f32_e32 v38, v38
	v_rcp_f32_e32 v39, v39
	v_rcp_f32_e32 v40, v40
	v_rcp_f32_e32 v41, v41
	v_pk_mul_f32 v[18:19], v[18:19], v[34:35]
	v_pk_mul_f32 v[20:21], v[20:21], v[36:37]
	v_pk_mul_f32 v[22:23], v[22:23], v[38:39]
	v_pk_mul_f32 v[24:25], v[24:25], v[40:41]
	v_pk_mul_f32 v[18:19], v[26:27], v[18:19]
	v_pk_mul_f32 v[20:21], v[28:29], v[20:21]
	v_pk_mul_f32 v[22:23], v[30:31], v[22:23]
	v_pk_mul_f32 v[24:25], v[32:33], v[24:25]
	v_cvt_pk_bf16_f32 v34, v18, v19
	v_cvt_pk_bf16_f32 v35, v20, v21
	v_cvt_pk_bf16_f32 v36, v22, v23
	v_cvt_pk_bf16_f32 v37, v24, v25
	global_store_dwordx4 v[50:51], v[34:37], off nt
	s_and_b64 vcc, exec, s[78:79]
	s_cbranch_vccz .Luc_skip2
	v_mov_b64_e32 v[82:83], v[2:3]
	v_mov_b64_e32 v[84:85], v[4:5]
	v_mov_b64_e32 v[86:87], v[6:7]
	v_mov_b64_e32 v[88:89], v[8:9]
	v_mov_b64_e32 v[90:91], v[10:11]
	v_mov_b64_e32 v[92:93], v[12:13]
	v_mov_b64_e32 v[94:95], v[14:15]
	v_mov_b64_e32 v[96:97], v[16:17]
.Luc_skip2:
	s_or_b64 exec, exec, s[28:29]
	v_readlane_b32 s28, v255, 19
	v_lshl_add_u64 v[50:51], v[50:51], 0, s[38:39]
	s_waitcnt lgkmcnt(0)
	v_lshlrev_b32_e32 v98, 16, v122
	v_and_b32_e32 v99, 0xffff0000, v122
	v_lshlrev_b32_e32 v100, 16, v123
	v_and_b32_e32 v101, 0xffff0000, v123
	v_lshlrev_b32_e32 v102, 16, v124
	v_and_b32_e32 v103, 0xffff0000, v124
	v_lshlrev_b32_e32 v104, 16, v125
	v_and_b32_e32 v105, 0xffff0000, v125
	v_lshlrev_b32_e32 v106, 16, v126
	v_and_b32_e32 v107, 0xffff0000, v126
	v_lshlrev_b32_e32 v108, 16, v127
	v_and_b32_e32 v109, 0xffff0000, v127
	v_lshlrev_b32_e32 v110, 16, v128
	v_and_b32_e32 v111, 0xffff0000, v128
	v_lshlrev_b32_e32 v112, 16, v129
	v_and_b32_e32 v113, 0xffff0000, v129
	ds_read_b128 v[114:117], v54 offset:3264
	ds_read_b128 v[118:121], v54 offset:3520
	s_movk_i32 s6, 252
	v_cmp_gt_i32_e32 vcc, s6, v49
	s_sub_i32 s6, s28, 3
	v_cmp_gt_i32_e64 s[6:7], s6, v45
	s_and_b64 s[6:7], vcc, s[6:7]
	s_and_saveexec_b64 s[28:29], s[6:7]
	s_cbranch_execz .Luc_skip3
	v_add_u32_e32 v52, 3, v45
	v_mov_b32_e32 v53, 0xff
	v_cmp_gt_i32_e32 vcc, s49, v52
	v_mov_b32_e32 v46, 0xfff
	s_nop 0
	v_cndmask_b32_e32 v53, v53, v46, vcc
	v_and_b32_e32 v52, v52, v53
	v_cmp_ne_u32_e32 vcc, 0, v52
	v_cmp_ne_u32_e64 s[6:7], v52, v53
	s_mov_b64 s[78:79], 0
	s_and_b64 s[76:77], vcc, s[6:7]
	s_xor_b64 s[76:77], s[76:77], exec
	s_cbranch_scc0 .Luc_fast3
	v_cndmask_b32_e32 v66, 0, v66, vcc
	v_cndmask_b32_e32 v67, 0, v67, vcc
	v_cndmask_b32_e32 v68, 0, v68, vcc
	v_cndmask_b32_e32 v69, 0, v69, vcc
	v_cndmask_b32_e32 v70, 0, v70, vcc
	v_cndmask_b32_e32 v71, 0, v71, vcc
	v_cndmask_b32_e32 v72, 0, v72, vcc
	v_cndmask_b32_e32 v73, 0, v73, vcc
	v_cndmask_b32_e32 v74, 0, v74, vcc
	v_cndmask_b32_e32 v75, 0, v75, vcc
	v_cndmask_b32_e32 v76, 0, v76, vcc
	v_cndmask_b32_e32 v77, 0, v77, vcc
	v_cndmask_b32_e32 v78, 0, v78, vcc
	v_cndmask_b32_e32 v79, 0, v79, vcc
	v_cndmask_b32_e32 v80, 0, v80, vcc
	v_cndmask_b32_e32 v81, 0, v81, vcc
	v_mov_b64_e32 v[2:3], v[98:99]
	v_mov_b64_e32 v[4:5], v[100:101]
	v_mov_b64_e32 v[6:7], v[102:103]
	v_mov_b64_e32 v[8:9], v[104:105]
	v_mov_b64_e32 v[10:11], v[106:107]
	v_mov_b64_e32 v[12:13], v[108:109]
	v_mov_b64_e32 v[14:15], v[110:111]
	v_mov_b64_e32 v[16:17], v[112:113]
	v_cndmask_b32_e64 v98, 0, v98, s[6:7]
	v_cndmask_b32_e64 v99, 0, v99, s[6:7]
	v_cndmask_b32_e64 v100, 0, v100, s[6:7]
	v_cndmask_b32_e64 v101, 0, v101, s[6:7]
	v_cndmask_b32_e64 v102, 0, v102, s[6:7]
	v_cndmask_b32_e64 v103, 0, v103, s[6:7]
	v_cndmask_b32_e64 v104, 0, v104, s[6:7]
	v_cndmask_b32_e64 v105, 0, v105, s[6:7]
	v_cndmask_b32_e64 v106, 0, v106, s[6:7]
	v_cndmask_b32_e64 v107, 0, v107, s[6:7]
	v_cndmask_b32_e64 v108, 0, v108, s[6:7]
	v_cndmask_b32_e64 v109, 0, v109, s[6:7]
	v_cndmask_b32_e64 v110, 0, v110, s[6:7]
	v_cndmask_b32_e64 v111, 0, v111, s[6:7]
	v_cndmask_b32_e64 v112, 0, v112, s[6:7]
	v_cndmask_b32_e64 v113, 0, v113, s[6:7]
	s_mov_b64 s[78:79], -1

.Luc_skip3:
	s_or_b64 exec, exec, s[28:29]
	v_readlane_b32 s28, v255, 19
	v_lshl_add_u64 v[50:51], v[50:51], 0, s[38:39]
	s_waitcnt lgkmcnt(0)
	v_lshlrev_b32_e32 v66, 16, v114
	v_and_b32_e32 v67, 0xffff0000, v114
	v_lshlrev_b32_e32 v68, 16, v115
	v_and_b32_e32 v69, 0xffff0000, v115
	v_lshlrev_b32_e32 v70, 16, v116
	v_and_b32_e32 v71, 0xffff0000, v116
	v_lshlrev_b32_e32 v72, 16, v117
	v_and_b32_e32 v73, 0xffff0000, v117
	v_lshlrev_b32_e32 v74, 16, v118
	v_and_b32_e32 v75, 0xffff0000, v118
	v_lshlrev_b32_e32 v76, 16, v119
	v_and_b32_e32 v77, 0xffff0000, v119
	v_lshlrev_b32_e32 v78, 16, v120
	v_and_b32_e32 v79, 0xffff0000, v120
	v_lshlrev_b32_e32 v80, 16, v121
	v_and_b32_e32 v81, 0xffff0000, v121
	ds_read_b128 v[122:125], v54 offset:3808
	ds_read_b128 v[126:129], v54 offset:4064
	s_movk_i32 s6, 251
	v_cmp_gt_i32_e32 vcc, s6, v49
	s_sub_i32 s6, s28, 4
	v_cmp_gt_i32_e64 s[6:7], s6, v45
	s_and_b64 s[6:7], vcc, s[6:7]
	s_and_saveexec_b64 s[28:29], s[6:7]
	s_cbranch_execz .Luc_skip4
	v_add_u32_e32 v52, 4, v45
	v_mov_b32_e32 v53, 0xff
	v_cmp_gt_i32_e32 vcc, s49, v52
	v_mov_b32_e32 v46, 0xfff
	s_nop 0
	v_cndmask_b32_e32 v53, v53, v46, vcc
	v_and_b32_e32 v52, v52, v53
	v_cmp_ne_u32_e32 vcc, 0, v52
	v_cmp_ne_u32_e64 s[6:7], v52, v53
	s_mov_b64 s[78:79], 0
	s_and_b64 s[76:77], vcc, s[6:7]
	s_xor_b64 s[76:77], s[76:77], exec
	s_cbranch_scc0 .Luc_fast4
	v_cndmask_b32_e32 v82, 0, v82, vcc
	v_cndmask_b32_e32 v83, 0, v83, vcc
	v_cndmask_b32_e32 v84, 0, v84, vcc
	v_cndmask_b32_e32 v85, 0, v85, vcc
	v_cndmask_b32_e32 v86, 0, v86, vcc
	v_cndmask_b32_e32 v87, 0, v87, vcc
	v_cndmask_b32_e32 v88, 0, v88, vcc
	v_cndmask_b32_e32 v89, 0, v89, vcc
	v_cndmask_b32_e32 v90, 0, v90, vcc
	v_cndmask_b32_e32 v91, 0, v91, vcc
	v_cndmask_b32_e32 v92, 0, v92, vcc
	v_cndmask_b32_e32 v93, 0, v93, vcc
	v_cndmask_b32_e32 v94, 0, v94, vcc
	v_cndmask_b32_e32 v95, 0, v95, vcc
	v_cndmask_b32_e32 v96, 0, v96, vcc
	v_cndmask_b32_e32 v97, 0, v97, vcc
	v_mov_b64_e32 v[2:3], v[66:67]
	v_mov_b64_e32 v[4:5], v[68:69]
	v_mov_b64_e32 v[6:7], v[70:71]
	v_mov_b64_e32 v[8:9], v[72:73]
	v_mov_b64_e32 v[10:11], v[74:75]
	v_mov_b64_e32 v[12:13], v[76:77]
	v_mov_b64_e32 v[14:15], v[78:79]
	v_mov_b64_e32 v[16:17], v[80:81]
	v_cndmask_b32_e64 v66, 0, v66, s[6:7]
	v_cndmask_b32_e64 v67, 0, v67, s[6:7]
	v_cndmask_b32_e64 v68, 0, v68, s[6:7]
	v_cndmask_b32_e64 v69, 0, v69, s[6:7]
	v_cndmask_b32_e64 v70, 0, v70, s[6:7]
	v_cndmask_b32_e64 v71, 0, v71, s[6:7]
	v_cndmask_b32_e64 v72, 0, v72, s[6:7]
	v_cndmask_b32_e64 v73, 0, v73, s[6:7]
	v_cndmask_b32_e64 v74, 0, v74, s[6:7]
	v_cndmask_b32_e64 v75, 0, v75, s[6:7]
	v_cndmask_b32_e64 v76, 0, v76, s[6:7]
	v_cndmask_b32_e64 v77, 0, v77, s[6:7]
	v_cndmask_b32_e64 v78, 0, v78, s[6:7]
	v_cndmask_b32_e64 v79, 0, v79, s[6:7]
	v_cndmask_b32_e64 v80, 0, v80, s[6:7]
	v_cndmask_b32_e64 v81, 0, v81, s[6:7]
	s_mov_b64 s[78:79], -1

.Luc_skip4:
	s_or_b64 exec, exec, s[28:29]
	v_readlane_b32 s28, v255, 19
	v_lshl_add_u64 v[50:51], v[50:51], 0, s[38:39]
	s_waitcnt lgkmcnt(0)
	v_lshlrev_b32_e32 v82, 16, v122
	v_and_b32_e32 v83, 0xffff0000, v122
	v_lshlrev_b32_e32 v84, 16, v123
	v_and_b32_e32 v85, 0xffff0000, v123
	v_lshlrev_b32_e32 v86, 16, v124
	v_and_b32_e32 v87, 0xffff0000, v124
	v_lshlrev_b32_e32 v88, 16, v125
	v_and_b32_e32 v89, 0xffff0000, v125
	v_lshlrev_b32_e32 v90, 16, v126
	v_and_b32_e32 v91, 0xffff0000, v126
	v_lshlrev_b32_e32 v92, 16, v127
	v_and_b32_e32 v93, 0xffff0000, v127
	v_lshlrev_b32_e32 v94, 16, v128
	v_and_b32_e32 v95, 0xffff0000, v128
	v_lshlrev_b32_e32 v96, 16, v129
	v_and_b32_e32 v97, 0xffff0000, v129
	ds_read_b128 v[114:117], v54 offset:4352
	ds_read_b128 v[118:121], v54 offset:4608
	s_movk_i32 s6, 250
	v_cmp_gt_i32_e32 vcc, s6, v49
	s_sub_i32 s6, s28, 5
	v_cmp_gt_i32_e64 s[6:7], s6, v45
	s_and_b64 s[6:7], vcc, s[6:7]
	s_and_saveexec_b64 s[28:29], s[6:7]
	s_cbranch_execz .Luc_skip5
	v_add_u32_e32 v52, 5, v45
	v_mov_b32_e32 v53, 0xff
	v_cmp_gt_i32_e32 vcc, s49, v52
	v_mov_b32_e32 v46, 0xfff
	s_nop 0
	v_cndmask_b32_e32 v53, v53, v46, vcc
	v_and_b32_e32 v52, v52, v53
	v_cmp_ne_u32_e32 vcc, 0, v52
	v_cmp_ne_u32_e64 s[6:7], v52, v53
	s_mov_b64 s[78:79], 0
	s_and_b64 s[76:77], vcc, s[6:7]
	s_xor_b64 s[76:77], s[76:77], exec
	s_cbranch_scc0 .Luc_fast5
	v_cndmask_b32_e32 v98, 0, v98, vcc
	v_cndmask_b32_e32 v99, 0, v99, vcc
	v_cndmask_b32_e32 v100, 0, v100, vcc
	v_cndmask_b32_e32 v101, 0, v101, vcc
	v_cndmask_b32_e32 v102, 0, v102, vcc
	v_cndmask_b32_e32 v103, 0, v103, vcc
	v_cndmask_b32_e32 v104, 0, v104, vcc
	v_cndmask_b32_e32 v105, 0, v105, vcc
	v_cndmask_b32_e32 v106, 0, v106, vcc
	v_cndmask_b32_e32 v107, 0, v107, vcc
	v_cndmask_b32_e32 v108, 0, v108, vcc
	v_cndmask_b32_e32 v109, 0, v109, vcc
	v_cndmask_b32_e32 v110, 0, v110, vcc
	v_cndmask_b32_e32 v111, 0, v111, vcc
	v_cndmask_b32_e32 v112, 0, v112, vcc
	v_cndmask_b32_e32 v113, 0, v113, vcc
	v_mov_b64_e32 v[2:3], v[82:83]
	v_mov_b64_e32 v[4:5], v[84:85]
	v_mov_b64_e32 v[6:7], v[86:87]
	v_mov_b64_e32 v[8:9], v[88:89]
	v_mov_b64_e32 v[10:11], v[90:91]
	v_mov_b64_e32 v[12:13], v[92:93]
	v_mov_b64_e32 v[14:15], v[94:95]
	v_mov_b64_e32 v[16:17], v[96:97]
	v_cndmask_b32_e64 v82, 0, v82, s[6:7]
	v_cndmask_b32_e64 v83, 0, v83, s[6:7]
	v_cndmask_b32_e64 v84, 0, v84, s[6:7]
	v_cndmask_b32_e64 v85, 0, v85, s[6:7]
	v_cndmask_b32_e64 v86, 0, v86, s[6:7]
	v_cndmask_b32_e64 v87, 0, v87, s[6:7]
	v_cndmask_b32_e64 v88, 0, v88, s[6:7]
	v_cndmask_b32_e64 v89, 0, v89, s[6:7]
	v_cndmask_b32_e64 v90, 0, v90, s[6:7]
	v_cndmask_b32_e64 v91, 0, v91, s[6:7]
	v_cndmask_b32_e64 v92, 0, v92, s[6:7]
	v_cndmask_b32_e64 v93, 0, v93, s[6:7]
	v_cndmask_b32_e64 v94, 0, v94, s[6:7]
	v_cndmask_b32_e64 v95, 0, v95, s[6:7]
	v_cndmask_b32_e64 v96, 0, v96, s[6:7]
	v_cndmask_b32_e64 v97, 0, v97, s[6:7]
	s_mov_b64 s[78:79], -1

.Luc_skip5:
	s_or_b64 exec, exec, s[28:29]
	v_readlane_b32 s28, v255, 19
	v_lshl_add_u64 v[50:51], v[50:51], 0, s[38:39]
	s_waitcnt lgkmcnt(0)
	v_lshlrev_b32_e32 v98, 16, v114
	v_and_b32_e32 v99, 0xffff0000, v114
	v_lshlrev_b32_e32 v100, 16, v115
	v_and_b32_e32 v101, 0xffff0000, v115
	v_lshlrev_b32_e32 v102, 16, v116
	v_and_b32_e32 v103, 0xffff0000, v116
	v_lshlrev_b32_e32 v104, 16, v117
	v_and_b32_e32 v105, 0xffff0000, v117
	v_lshlrev_b32_e32 v106, 16, v118
	v_and_b32_e32 v107, 0xffff0000, v118
	v_lshlrev_b32_e32 v108, 16, v119
	v_and_b32_e32 v109, 0xffff0000, v119
	v_lshlrev_b32_e32 v110, 16, v120
	v_and_b32_e32 v111, 0xffff0000, v120
	v_lshlrev_b32_e32 v112, 16, v121
	v_and_b32_e32 v113, 0xffff0000, v121
	ds_read_b128 v[122:125], v54 offset:4896
	ds_read_b128 v[126:129], v54 offset:5152
	s_movk_i32 s6, 249
	v_cmp_gt_i32_e32 vcc, s6, v49
	s_sub_i32 s6, s28, 6
	v_cmp_gt_i32_e64 s[6:7], s6, v45
	s_and_b64 s[6:7], vcc, s[6:7]
	s_and_saveexec_b64 s[28:29], s[6:7]
	s_cbranch_execz .Luc_skip6
	v_add_u32_e32 v52, 6, v45
	v_mov_b32_e32 v53, 0xff
	v_cmp_gt_i32_e32 vcc, s49, v52
	v_mov_b32_e32 v46, 0xfff
	s_nop 0
	v_cndmask_b32_e32 v53, v53, v46, vcc
	v_and_b32_e32 v52, v52, v53
	v_cmp_ne_u32_e32 vcc, 0, v52
	v_cmp_ne_u32_e64 s[6:7], v52, v53
	s_mov_b64 s[78:79], 0
	s_and_b64 s[76:77], vcc, s[6:7]
	s_xor_b64 s[76:77], s[76:77], exec
	s_cbranch_scc0 .Luc_fast6
	v_cndmask_b32_e32 v66, 0, v66, vcc
	v_cndmask_b32_e32 v67, 0, v67, vcc
	v_cndmask_b32_e32 v68, 0, v68, vcc
	v_cndmask_b32_e32 v69, 0, v69, vcc
	v_cndmask_b32_e32 v70, 0, v70, vcc
	v_cndmask_b32_e32 v71, 0, v71, vcc
	v_cndmask_b32_e32 v72, 0, v72, vcc
	v_cndmask_b32_e32 v73, 0, v73, vcc
	v_cndmask_b32_e32 v74, 0, v74, vcc
	v_cndmask_b32_e32 v75, 0, v75, vcc
	v_cndmask_b32_e32 v76, 0, v76, vcc
	v_cndmask_b32_e32 v77, 0, v77, vcc
	v_cndmask_b32_e32 v78, 0, v78, vcc
	v_cndmask_b32_e32 v79, 0, v79, vcc
	v_cndmask_b32_e32 v80, 0, v80, vcc
	v_cndmask_b32_e32 v81, 0, v81, vcc
	v_mov_b64_e32 v[2:3], v[98:99]
	v_mov_b64_e32 v[4:5], v[100:101]
	v_mov_b64_e32 v[6:7], v[102:103]
	v_mov_b64_e32 v[8:9], v[104:105]
	v_mov_b64_e32 v[10:11], v[106:107]
	v_mov_b64_e32 v[12:13], v[108:109]
	v_mov_b64_e32 v[14:15], v[110:111]
	v_mov_b64_e32 v[16:17], v[112:113]
	v_cndmask_b32_e64 v98, 0, v98, s[6:7]
	v_cndmask_b32_e64 v99, 0, v99, s[6:7]
	v_cndmask_b32_e64 v100, 0, v100, s[6:7]
	v_cndmask_b32_e64 v101, 0, v101, s[6:7]
	v_cndmask_b32_e64 v102, 0, v102, s[6:7]
	v_cndmask_b32_e64 v103, 0, v103, s[6:7]
	v_cndmask_b32_e64 v104, 0, v104, s[6:7]
	v_cndmask_b32_e64 v105, 0, v105, s[6:7]
	v_cndmask_b32_e64 v106, 0, v106, s[6:7]
	v_cndmask_b32_e64 v107, 0, v107, s[6:7]
	v_cndmask_b32_e64 v108, 0, v108, s[6:7]
	v_cndmask_b32_e64 v109, 0, v109, s[6:7]
	v_cndmask_b32_e64 v110, 0, v110, s[6:7]
	v_cndmask_b32_e64 v111, 0, v111, s[6:7]
	v_cndmask_b32_e64 v112, 0, v112, s[6:7]
	v_cndmask_b32_e64 v113, 0, v113, s[6:7]
	s_mov_b64 s[78:79], -1

.Luc_skip6:
	s_or_b64 exec, exec, s[28:29]
	v_readlane_b32 s28, v255, 19
	v_lshl_add_u64 v[50:51], v[50:51], 0, s[38:39]
	s_waitcnt lgkmcnt(0)
	v_lshlrev_b32_e32 v66, 16, v122
	v_and_b32_e32 v67, 0xffff0000, v122
	v_lshlrev_b32_e32 v68, 16, v123
	v_and_b32_e32 v69, 0xffff0000, v123
	v_lshlrev_b32_e32 v70, 16, v124
	v_and_b32_e32 v71, 0xffff0000, v124
	v_lshlrev_b32_e32 v72, 16, v125
	v_and_b32_e32 v73, 0xffff0000, v125
	v_lshlrev_b32_e32 v74, 16, v126
	v_and_b32_e32 v75, 0xffff0000, v126
	v_lshlrev_b32_e32 v76, 16, v127
	v_and_b32_e32 v77, 0xffff0000, v127
	v_lshlrev_b32_e32 v78, 16, v128
	v_and_b32_e32 v79, 0xffff0000, v128
	v_lshlrev_b32_e32 v80, 16, v129
	v_and_b32_e32 v81, 0xffff0000, v129
	s_movk_i32 s6, 248
	v_cmp_gt_i32_e32 vcc, s6, v49
	s_sub_i32 s6, s28, 7
	v_cmp_gt_i32_e64 s[6:7], s6, v45
	s_and_b64 s[6:7], vcc, s[6:7]
	s_and_saveexec_b64 s[28:29], s[6:7]
	s_cbranch_execz .Luc_skip7
	v_add_u32_e32 v52, 7, v45
	v_mov_b32_e32 v53, 0xff
	v_cmp_gt_i32_e32 vcc, s49, v52
	v_mov_b32_e32 v46, 0xfff
	s_nop 0
	v_cndmask_b32_e32 v53, v53, v46, vcc
	v_and_b32_e32 v52, v52, v53
	v_cmp_ne_u32_e32 vcc, 0, v52
	v_cmp_ne_u32_e64 s[6:7], v52, v53
	s_mov_b64 s[78:79], 0
	s_and_b64 s[76:77], vcc, s[6:7]
	s_xor_b64 s[76:77], s[76:77], exec
	s_cbranch_scc0 .Luc_fast7
	v_cndmask_b32_e32 v82, 0, v82, vcc
	v_cndmask_b32_e32 v83, 0, v83, vcc
	v_cndmask_b32_e32 v84, 0, v84, vcc
	v_cndmask_b32_e32 v85, 0, v85, vcc
	v_cndmask_b32_e32 v86, 0, v86, vcc
	v_cndmask_b32_e32 v87, 0, v87, vcc
	v_cndmask_b32_e32 v88, 0, v88, vcc
	v_cndmask_b32_e32 v89, 0, v89, vcc
	v_cndmask_b32_e32 v90, 0, v90, vcc
	v_cndmask_b32_e32 v91, 0, v91, vcc
	v_cndmask_b32_e32 v92, 0, v92, vcc
	v_cndmask_b32_e32 v93, 0, v93, vcc
	v_cndmask_b32_e32 v94, 0, v94, vcc
	v_cndmask_b32_e32 v95, 0, v95, vcc
	v_cndmask_b32_e32 v96, 0, v96, vcc
	v_cndmask_b32_e32 v97, 0, v97, vcc
	v_mov_b64_e32 v[2:3], v[66:67]
	v_mov_b64_e32 v[4:5], v[68:69]
	v_mov_b64_e32 v[6:7], v[70:71]
	v_mov_b64_e32 v[8:9], v[72:73]
	v_mov_b64_e32 v[10:11], v[74:75]
	v_mov_b64_e32 v[12:13], v[76:77]
	v_mov_b64_e32 v[14:15], v[78:79]
	v_mov_b64_e32 v[16:17], v[80:81]
	v_cndmask_b32_e64 v66, 0, v66, s[6:7]
	v_cndmask_b32_e64 v67, 0, v67, s[6:7]
	v_cndmask_b32_e64 v68, 0, v68, s[6:7]
	v_cndmask_b32_e64 v69, 0, v69, s[6:7]
	v_cndmask_b32_e64 v70, 0, v70, s[6:7]
	v_cndmask_b32_e64 v71, 0, v71, s[6:7]
	v_cndmask_b32_e64 v72, 0, v72, s[6:7]
	v_cndmask_b32_e64 v73, 0, v73, s[6:7]
	v_cndmask_b32_e64 v74, 0, v74, s[6:7]
	v_cndmask_b32_e64 v75, 0, v75, s[6:7]
	v_cndmask_b32_e64 v76, 0, v76, s[6:7]
	v_cndmask_b32_e64 v77, 0, v77, s[6:7]
	v_cndmask_b32_e64 v78, 0, v78, s[6:7]
	v_cndmask_b32_e64 v79, 0, v79, s[6:7]
	v_cndmask_b32_e64 v80, 0, v80, s[6:7]
	v_cndmask_b32_e64 v81, 0, v81, s[6:7]
	s_mov_b64 s[78:79], -1

.Luc_skip7:
	s_or_b64 exec, exec, s[28:29]
	v_readlane_b32 s28, v255, 19
	v_readlane_b32 s66, v255, 2
	s_movk_i32 s49, 0x4000
	s_mov_b32 s56, 0xa000
	s_mov_b32 s76, 0x4d000
	s_movk_i32 s57, 0x1ff
	v_readlane_b32 s67, v255, 3
	v_readlane_b32 s81, v254, 62
	s_mov_b32 s77, 0x1c000
	s_mov_b32 s78, 0xe000
	s_mov_b32 s79, 0x26000
	s_mov_b32 s85, 0x34000
	s_mov_b32 s93, 0x38000
	s_mov_b64 s[6:7], 0
	s_branch .LBB0_148
